# sc1 (write-through, drop from L2) on the MLP-in epilogue's hidden-activation stores
# baseline (speedup 1.0000x reference)
.LBB0_256:
	v_add_u32_e32 v138, 0x10000, v141
	ds_read_b128 v[144:147], v138
	ds_read_b128 v[148:151], v138 offset:1024
	ds_read_b128 v[152:155], v138 offset:2048
	ds_read_b128 v[156:159], v138 offset:3072
	ds_read_b128 v[160:163], v142
	ds_read_b128 v[164:167], v142 offset:1024
	ds_read_b128 v[168:171], v142 offset:2048
	ds_read_b128 v[172:175], v142 offset:3072
	ds_read_b128 v[176:179], v142 offset:4096
	ds_read_b128 v[180:183], v142 offset:5120
	ds_read_b128 v[184:187], v142 offset:6144
	ds_read_b128 v[188:191], v142 offset:7168
	v_add_u32_e32 v138, 0x14000, v141
	ds_read_b128 v[194:197], v138
	ds_read_b128 v[198:201], v138 offset:1024
	ds_read_b128 v[202:205], v138 offset:2048
	ds_read_b128 v[206:209], v138 offset:3072
	s_add_u32 s4, s2, 0xfff80080
	s_addc_u32 s5, s3, -1
	s_add_i32 s9, 0, 0x10000
	s_cmp_eq_u32 s69, 28
	s_cselect_b32 s49, s35, s5
	s_cselect_b32 s48, s34, s4
	s_cselect_b32 s5, s37, s29
	s_cselect_b32 s4, s36, s15
	v_lshl_add_u64 v[138:139], s[2:3], 0, v[134:135]
	s_add_i32 m0, s39, 0xc000
	s_nop 0
	global_load_lds_dwordx4 v[138:139], off
	v_lshl_add_u64 v[138:139], s[2:3], 0, v[136:137]
	s_add_i32 m0, s39, 0xe000
	s_nop 0
	global_load_lds_dwordx4 v[138:139], off
	s_waitcnt vmcnt(8)
	s_waitcnt lgkmcnt(0)
	s_barrier
	s_setprio 1
	v_mfma_f32_16x16x32_bf16 v[124:127], v[144:147], v[160:163], v[124:127]
	v_mfma_f32_16x16x32_bf16 v[120:123], v[152:155], v[160:163], v[120:123]
	v_mfma_f32_16x16x32_bf16 v[108:111], v[144:147], v[168:171], v[108:111]
	v_mfma_f32_16x16x32_bf16 v[104:107], v[152:155], v[168:171], v[104:107]
	v_mfma_f32_16x16x32_bf16 v[92:95], v[144:147], v[176:179], v[92:95]
	v_mfma_f32_16x16x32_bf16 v[88:91], v[152:155], v[176:179], v[88:91]
	v_mfma_f32_16x16x32_bf16 v[76:79], v[144:147], v[184:187], v[76:79]
	v_mfma_f32_16x16x32_bf16 v[72:75], v[152:155], v[184:187], v[72:75]
	v_mfma_f32_16x16x32_bf16 v[124:127], v[148:151], v[164:167], v[124:127]
	v_mfma_f32_16x16x32_bf16 v[120:123], v[156:159], v[164:167], v[120:123]
	v_mfma_f32_16x16x32_bf16 v[108:111], v[148:151], v[172:175], v[108:111]
	v_mfma_f32_16x16x32_bf16 v[104:107], v[156:159], v[172:175], v[104:107]
	v_mfma_f32_16x16x32_bf16 v[92:95], v[148:151], v[180:183], v[92:95]
	v_mfma_f32_16x16x32_bf16 v[88:91], v[156:159], v[180:183], v[88:91]
	v_mfma_f32_16x16x32_bf16 v[76:79], v[148:151], v[188:191], v[76:79]
	v_mfma_f32_16x16x32_bf16 v[72:75], v[156:159], v[188:191], v[72:75]
	v_mfma_f32_16x16x32_bf16 v[116:119], v[194:197], v[160:163], v[116:119]
	v_mfma_f32_16x16x32_bf16 v[112:115], v[202:205], v[160:163], v[112:115]
	v_mfma_f32_16x16x32_bf16 v[100:103], v[194:197], v[168:171], v[100:103]
	v_mfma_f32_16x16x32_bf16 v[96:99], v[202:205], v[168:171], v[96:99]
	v_mfma_f32_16x16x32_bf16 v[84:87], v[194:197], v[176:179], v[84:87]
	v_mfma_f32_16x16x32_bf16 v[80:83], v[202:205], v[176:179], v[80:83]
	v_mfma_f32_16x16x32_bf16 v[68:71], v[194:197], v[184:187], v[68:71]
	v_mfma_f32_16x16x32_bf16 v[64:67], v[202:205], v[184:187], v[64:67]
	v_mfma_f32_16x16x32_bf16 v[116:119], v[198:201], v[164:167], v[116:119]
	v_mfma_f32_16x16x32_bf16 v[112:115], v[206:209], v[164:167], v[112:115]
	v_mfma_f32_16x16x32_bf16 v[100:103], v[198:201], v[172:175], v[100:103]
	v_mfma_f32_16x16x32_bf16 v[96:99], v[206:209], v[172:175], v[96:99]
	v_mfma_f32_16x16x32_bf16 v[84:87], v[198:201], v[180:183], v[84:87]
	v_mfma_f32_16x16x32_bf16 v[80:83], v[206:209], v[180:183], v[80:83]
	v_mfma_f32_16x16x32_bf16 v[68:71], v[198:201], v[188:191], v[68:71]
	v_mfma_f32_16x16x32_bf16 v[64:67], v[206:209], v[188:191], v[64:67]
	s_setprio 0
	s_barrier
	ds_read_b128 v[160:163], v142 offset:16384
	ds_read_b128 v[164:167], v142 offset:17408
	ds_read_b128 v[168:171], v142 offset:18432
	ds_read_b128 v[172:175], v142 offset:19456
	ds_read_b128 v[176:179], v142 offset:20480
	ds_read_b128 v[180:183], v142 offset:21504
	ds_read_b128 v[184:187], v142 offset:22528
	ds_read_b128 v[188:191], v142 offset:23552
	s_add_i32 s71, 0, 0x14000
	s_add_i32 s9, s9, s50
	v_lshl_add_u64 v[138:139], s[4:5], 0, v[192:193]
	s_mov_b32 m0, s9
	v_lshl_add_u64 v[210:211], s[4:5], 0, v[128:129]
	global_load_lds_dwordx4 v[138:139], off
	s_add_i32 m0, s9, 0x2000
	s_nop 0
	global_load_lds_dwordx4 v[210:211], off
	s_mov_b32 m0, s39
	v_lshl_add_u64 v[212:213], s[48:49], 0, v[132:133]
	global_load_lds_dwordx4 v[212:213], off
	v_lshl_add_u64 v[214:215], s[48:49], 0, v[130:131]
	s_mov_b32 m0, s54
	s_nop 0
	global_load_lds_dwordx4 v[214:215], off
	s_add_u32 s46, s4, 0x80000
	s_addc_u32 s47, s5, 0
	s_add_i32 s9, s71, s50
	v_lshl_add_u64 v[218:219], s[46:47], 0, v[192:193]
	s_mov_b32 m0, s9
	s_nop 0
	global_load_lds_dwordx4 v[218:219], off
	v_lshl_add_u64 v[220:221], s[46:47], 0, v[128:129]
	s_add_i32 m0, s9, 0x2000
	s_nop 0
	global_load_lds_dwordx4 v[220:221], off
	s_waitcnt vmcnt(8)
	s_waitcnt lgkmcnt(0)
	s_barrier
	s_setprio 1
	v_mfma_f32_16x16x32_bf16 v[60:63], v[144:147], v[160:163], v[60:63]
	v_mfma_f32_16x16x32_bf16 v[56:59], v[152:155], v[160:163], v[56:59]
	v_mfma_f32_16x16x32_bf16 v[44:47], v[144:147], v[168:171], v[44:47]
	v_mfma_f32_16x16x32_bf16 v[40:43], v[152:155], v[168:171], v[40:43]
	v_mfma_f32_16x16x32_bf16 v[28:31], v[144:147], v[176:179], v[28:31]
	v_mfma_f32_16x16x32_bf16 v[24:27], v[152:155], v[176:179], v[24:27]
	v_mfma_f32_16x16x32_bf16 v[12:15], v[144:147], v[184:187], v[12:15]
	v_mfma_f32_16x16x32_bf16 v[8:11], v[152:155], v[184:187], v[8:11]
	v_mfma_f32_16x16x32_bf16 v[60:63], v[148:151], v[164:167], v[60:63]
	v_mfma_f32_16x16x32_bf16 v[56:59], v[156:159], v[164:167], v[56:59]
	v_mfma_f32_16x16x32_bf16 v[44:47], v[148:151], v[172:175], v[44:47]
	v_mfma_f32_16x16x32_bf16 v[40:43], v[156:159], v[172:175], v[40:43]
	v_mfma_f32_16x16x32_bf16 v[28:31], v[148:151], v[180:183], v[28:31]
	v_mfma_f32_16x16x32_bf16 v[24:27], v[156:159], v[180:183], v[24:27]
	v_mfma_f32_16x16x32_bf16 v[12:15], v[148:151], v[188:191], v[12:15]
	v_mfma_f32_16x16x32_bf16 v[8:11], v[156:159], v[188:191], v[8:11]
	v_mfma_f32_16x16x32_bf16 v[52:55], v[194:197], v[160:163], v[52:55]
	v_mfma_f32_16x16x32_bf16 v[48:51], v[202:205], v[160:163], v[48:51]
	v_mfma_f32_16x16x32_bf16 v[36:39], v[194:197], v[168:171], v[36:39]
	v_mfma_f32_16x16x32_bf16 v[32:35], v[202:205], v[168:171], v[32:35]
	v_mfma_f32_16x16x32_bf16 v[20:23], v[194:197], v[176:179], v[20:23]
	v_mfma_f32_16x16x32_bf16 v[16:19], v[202:205], v[176:179], v[16:19]
	v_mfma_f32_16x16x32_bf16 v[4:7], v[194:197], v[184:187], v[4:7]
	v_mfma_f32_16x16x32_bf16 v[0:3], v[202:205], v[184:187], v[0:3]
	v_mfma_f32_16x16x32_bf16 v[52:55], v[198:201], v[164:167], v[52:55]
	v_mfma_f32_16x16x32_bf16 v[48:51], v[206:209], v[164:167], v[48:51]
	v_mfma_f32_16x16x32_bf16 v[36:39], v[198:201], v[172:175], v[36:39]
	v_mfma_f32_16x16x32_bf16 v[32:35], v[206:209], v[172:175], v[32:35]
	v_mfma_f32_16x16x32_bf16 v[20:23], v[198:201], v[180:183], v[20:23]
	v_mfma_f32_16x16x32_bf16 v[16:19], v[206:209], v[180:183], v[16:19]
	v_mfma_f32_16x16x32_bf16 v[4:7], v[198:201], v[188:191], v[4:7]
	v_mfma_f32_16x16x32_bf16 v[0:3], v[206:209], v[188:191], v[0:3]
	s_setprio 0
	s_barrier
	v_add_u32_e32 v143, 0x18000, v141
	ds_read_b128 v[144:147], v143
	ds_read_b128 v[148:151], v143 offset:1024
	ds_read_b128 v[152:155], v143 offset:2048
	ds_read_b128 v[156:159], v143 offset:3072
	ds_read_b128 v[160:163], v142 offset:32768
	ds_read_b128 v[164:167], v142 offset:33792
	ds_read_b128 v[168:171], v142 offset:34816
	ds_read_b128 v[172:175], v142 offset:35840
	ds_read_b128 v[176:179], v142 offset:36864
	ds_read_b128 v[180:183], v142 offset:37888
	ds_read_b128 v[184:187], v142 offset:38912
	ds_read_b128 v[188:191], v142 offset:39936
	v_add_u32_e32 v143, 0x1c000, v141
	ds_read_b128 v[194:197], v143
	ds_read_b128 v[198:201], v143 offset:1024
	ds_read_b128 v[202:205], v143 offset:2048
	ds_read_b128 v[206:209], v143 offset:3072
	s_add_i32 s9, 0, 0x18000
	s_add_u32 s46, s48, 0x80000
	s_addc_u32 s47, s49, 0
	s_mov_b32 m0, s55
	v_lshl_add_u64 v[218:219], s[46:47], 0, v[132:133]
	global_load_lds_dwordx4 v[218:219], off
	v_lshl_add_u64 v[220:221], s[46:47], 0, v[130:131]
	s_mov_b32 m0, s58
	s_nop 0
	global_load_lds_dwordx4 v[220:221], off
	s_waitcnt vmcnt(8)
	s_waitcnt lgkmcnt(0)
	s_barrier
	s_setprio 1
	v_mfma_f32_16x16x32_bf16 v[124:127], v[144:147], v[160:163], v[124:127]
	v_mfma_f32_16x16x32_bf16 v[120:123], v[152:155], v[160:163], v[120:123]
	v_mfma_f32_16x16x32_bf16 v[108:111], v[144:147], v[168:171], v[108:111]
	v_mfma_f32_16x16x32_bf16 v[104:107], v[152:155], v[168:171], v[104:107]
	v_mfma_f32_16x16x32_bf16 v[92:95], v[144:147], v[176:179], v[92:95]
	v_mfma_f32_16x16x32_bf16 v[88:91], v[152:155], v[176:179], v[88:91]
	v_mfma_f32_16x16x32_bf16 v[76:79], v[144:147], v[184:187], v[76:79]
	v_mfma_f32_16x16x32_bf16 v[72:75], v[152:155], v[184:187], v[72:75]
	v_mfma_f32_16x16x32_bf16 v[124:127], v[148:151], v[164:167], v[124:127]
	v_mfma_f32_16x16x32_bf16 v[120:123], v[156:159], v[164:167], v[120:123]
	v_mfma_f32_16x16x32_bf16 v[108:111], v[148:151], v[172:175], v[108:111]
	v_mfma_f32_16x16x32_bf16 v[104:107], v[156:159], v[172:175], v[104:107]
	v_mfma_f32_16x16x32_bf16 v[92:95], v[148:151], v[180:183], v[92:95]
	v_mfma_f32_16x16x32_bf16 v[88:91], v[156:159], v[180:183], v[88:91]
	v_mfma_f32_16x16x32_bf16 v[76:79], v[148:151], v[188:191], v[76:79]
	v_mfma_f32_16x16x32_bf16 v[72:75], v[156:159], v[188:191], v[72:75]
	v_mfma_f32_16x16x32_bf16 v[116:119], v[194:197], v[160:163], v[116:119]
	v_mfma_f32_16x16x32_bf16 v[112:115], v[202:205], v[160:163], v[112:115]
	v_mfma_f32_16x16x32_bf16 v[100:103], v[194:197], v[168:171], v[100:103]
	v_mfma_f32_16x16x32_bf16 v[96:99], v[202:205], v[168:171], v[96:99]
	v_mfma_f32_16x16x32_bf16 v[84:87], v[194:197], v[176:179], v[84:87]
	v_mfma_f32_16x16x32_bf16 v[80:83], v[202:205], v[176:179], v[80:83]
	v_mfma_f32_16x16x32_bf16 v[68:71], v[194:197], v[184:187], v[68:71]
	v_mfma_f32_16x16x32_bf16 v[64:67], v[202:205], v[184:187], v[64:67]
	v_mfma_f32_16x16x32_bf16 v[116:119], v[198:201], v[164:167], v[116:119]
	v_mfma_f32_16x16x32_bf16 v[112:115], v[206:209], v[164:167], v[112:115]
	v_mfma_f32_16x16x32_bf16 v[100:103], v[198:201], v[172:175], v[100:103]
	v_mfma_f32_16x16x32_bf16 v[96:99], v[206:209], v[172:175], v[96:99]
	v_mfma_f32_16x16x32_bf16 v[84:87], v[198:201], v[180:183], v[84:87]
	v_mfma_f32_16x16x32_bf16 v[80:83], v[206:209], v[180:183], v[80:83]
	v_mfma_f32_16x16x32_bf16 v[68:71], v[198:201], v[188:191], v[68:71]
	v_mfma_f32_16x16x32_bf16 v[64:67], v[206:209], v[188:191], v[64:67]
	s_setprio 0
	s_barrier
	ds_read_b128 v[160:163], v142 offset:49152
	ds_read_b128 v[164:167], v142 offset:50176
	ds_read_b128 v[168:171], v142 offset:51200
	ds_read_b128 v[172:175], v142 offset:52224
	ds_read_b128 v[176:179], v142 offset:53248
	ds_read_b128 v[180:183], v142 offset:54272
	ds_read_b128 v[184:187], v142 offset:55296
	ds_read_b128 v[188:191], v142 offset:56320
	s_add_i32 s46, 0, 0x1c000
	s_add_i32 s9, s9, s50
	v_lshl_add_u64 v[138:139], v[138:139], 0, s[72:73]
	s_mov_b32 m0, s9
	s_nop 0
	global_load_lds_dwordx4 v[138:139], off
	v_lshl_add_u64 v[138:139], v[210:211], 0, s[72:73]
	s_add_i32 m0, s9, 0x2000
	s_nop 0
	global_load_lds_dwordx4 v[138:139], off
	s_mov_b32 m0, s59
	v_lshl_add_u64 v[138:139], v[212:213], 0, s[72:73]
	global_load_lds_dwordx4 v[138:139], off
	v_lshl_add_u64 v[138:139], v[214:215], 0, s[72:73]
	s_mov_b32 m0, s62
	s_nop 0
	global_load_lds_dwordx4 v[138:139], off
	s_add_u32 s4, s4, 0x80080
	s_addc_u32 s5, s5, 0
	s_add_i32 s9, s46, s50
	v_lshl_add_u64 v[138:139], s[4:5], 0, v[192:193]
	s_mov_b32 m0, s9
	s_nop 0
	global_load_lds_dwordx4 v[138:139], off
	v_lshl_add_u64 v[138:139], s[4:5], 0, v[128:129]
	s_add_i32 m0, s9, 0x2000
	s_nop 0
	global_load_lds_dwordx4 v[138:139], off
	s_waitcnt vmcnt(8)
	s_waitcnt lgkmcnt(0)
	s_barrier
	s_setprio 1
	v_mfma_f32_16x16x32_bf16 v[60:63], v[144:147], v[160:163], v[60:63]
	v_mfma_f32_16x16x32_bf16 v[56:59], v[152:155], v[160:163], v[56:59]
	v_mfma_f32_16x16x32_bf16 v[44:47], v[144:147], v[168:171], v[44:47]
	v_mfma_f32_16x16x32_bf16 v[40:43], v[152:155], v[168:171], v[40:43]
	v_mfma_f32_16x16x32_bf16 v[28:31], v[144:147], v[176:179], v[28:31]
	v_mfma_f32_16x16x32_bf16 v[24:27], v[152:155], v[176:179], v[24:27]
	v_mfma_f32_16x16x32_bf16 v[12:15], v[144:147], v[184:187], v[12:15]
	v_mfma_f32_16x16x32_bf16 v[8:11], v[152:155], v[184:187], v[8:11]
	v_mfma_f32_16x16x32_bf16 v[60:63], v[148:151], v[164:167], v[60:63]
	v_mfma_f32_16x16x32_bf16 v[56:59], v[156:159], v[164:167], v[56:59]
	v_mfma_f32_16x16x32_bf16 v[44:47], v[148:151], v[172:175], v[44:47]
	v_mfma_f32_16x16x32_bf16 v[40:43], v[156:159], v[172:175], v[40:43]
	v_mfma_f32_16x16x32_bf16 v[28:31], v[148:151], v[180:183], v[28:31]
	v_mfma_f32_16x16x32_bf16 v[24:27], v[156:159], v[180:183], v[24:27]
	v_mfma_f32_16x16x32_bf16 v[12:15], v[148:151], v[188:191], v[12:15]
	v_mfma_f32_16x16x32_bf16 v[8:11], v[156:159], v[188:191], v[8:11]
	v_mfma_f32_16x16x32_bf16 v[52:55], v[194:197], v[160:163], v[52:55]
	v_mfma_f32_16x16x32_bf16 v[48:51], v[202:205], v[160:163], v[48:51]
	v_mfma_f32_16x16x32_bf16 v[36:39], v[194:197], v[168:171], v[36:39]
	v_mfma_f32_16x16x32_bf16 v[32:35], v[202:205], v[168:171], v[32:35]
	v_mfma_f32_16x16x32_bf16 v[20:23], v[194:197], v[176:179], v[20:23]
	v_mfma_f32_16x16x32_bf16 v[16:19], v[202:205], v[176:179], v[16:19]
	v_mfma_f32_16x16x32_bf16 v[4:7], v[194:197], v[184:187], v[4:7]
	v_mfma_f32_16x16x32_bf16 v[0:3], v[202:205], v[184:187], v[0:3]
	v_mfma_f32_16x16x32_bf16 v[52:55], v[198:201], v[164:167], v[52:55]
	v_mfma_f32_16x16x32_bf16 v[48:51], v[206:209], v[164:167], v[48:51]
	v_mfma_f32_16x16x32_bf16 v[36:39], v[198:201], v[172:175], v[36:39]
	v_mfma_f32_16x16x32_bf16 v[32:35], v[206:209], v[172:175], v[32:35]
	v_mfma_f32_16x16x32_bf16 v[20:23], v[198:201], v[180:183], v[20:23]
	v_mfma_f32_16x16x32_bf16 v[16:19], v[206:209], v[180:183], v[16:19]
	v_mfma_f32_16x16x32_bf16 v[4:7], v[198:201], v[188:191], v[4:7]
	v_mfma_f32_16x16x32_bf16 v[0:3], v[206:209], v[188:191], v[0:3]
	s_setprio 0
	s_add_i32 s69, s69, 2
	s_add_u32 s2, s2, 0x100
	s_addc_u32 s3, s3, 0
	s_add_u32 s15, s15, 0x100
	s_addc_u32 s29, s29, 0
	s_cmp_gt_u32 s69, 29
	s_barrier
	s_cbranch_scc0 .LBB0_256
	s_lshl_b32 s2, s38, 8
	v_mov_b32 v138, v140
	s_add_i32 s2, s2, s63
	v_and_or_b32 v144, v138, 15, s2
	s_lshl_b32 s2, s67, 8
	v_ashrrev_i32_e32 v138, 1, v138
	v_max_f32_e32 v120, v120, v120
	s_or_b32 s2, s2, s64
	v_and_b32_e32 v138, -8, v138
	v_max_f32_e32 v120, 0, v120
	v_max_f32_e32 v121, v121, v121
	v_max_f32_e32 v122, v122, v122
	v_add_u32_e32 v138, s2, v138
	v_ashrrev_i32_e32 v145, 31, v144
	v_readlane_b32 s2, v252, 63
	v_mul_f32_e32 v143, v120, v120
	v_max_f32_e32 v120, v125, v125
	v_max_f32_e32 v121, 0, v121
	v_max_f32_e32 v122, 0, v122
	v_ashrrev_i32_e32 v139, 31, v138
	v_lshlrev_b64 v[146:147], 14, v[144:145]
	v_readlane_b32 s3, v253, 0
	v_max_f32_e32 v124, v124, v124
	v_max_f32_e32 v120, 0, v120
	v_mul_f32_e32 v125, v121, v121
	v_max_f32_e32 v121, v126, v126
	v_mul_f32_e32 v126, v122, v122
	v_max_f32_e32 v122, v127, v127
	v_max_f32_e32 v123, v123, v123
	v_lshl_add_u64 v[146:147], s[2:3], 0, v[146:147]
	v_lshlrev_b64 v[148:149], 1, v[138:139]
	v_max_f32_e32 v124, 0, v124
	v_mul_f32_e32 v120, v120, v120
	v_max_f32_e32 v121, 0, v121
	v_max_f32_e32 v122, 0, v122
	v_max_f32_e32 v123, 0, v123
	v_max_f32_e32 v112, v112, v112
	v_lshl_add_u64 v[138:139], v[146:147], 0, v[148:149]
	v_mul_f32_e32 v124, v124, v124
	v_mul_f32_e32 v121, v121, v121
	v_mul_f32_e32 v122, v122, v122
	v_mul_f32_e32 v123, v123, v123
	v_cvt_pk_bf16_f32 v120, v124, v120
	v_max_f32_e32 v112, 0, v112
	v_max_f32_e32 v113, v113, v113
	v_max_f32_e32 v114, v114, v114
	v_cvt_pk_bf16_f32 v121, v121, v122
	v_cvt_pk_bf16_f32 v122, v143, v125
	v_cvt_pk_bf16_f32 v123, v126, v123
	global_store_dwordx4 v[138:139], v[120:123], off sc1
	v_max_f32_e32 v113, 0, v113
	v_max_f32_e32 v114, 0, v114
	v_mul_f32_e32 v120, v112, v112
	v_max_f32_e32 v112, v117, v117
	v_max_f32_e32 v116, v116, v116
	v_max_f32_e32 v112, 0, v112
	v_mul_f32_e32 v117, v113, v113
	v_max_f32_e32 v113, v118, v118
	v_mul_f32_e32 v118, v114, v114
	v_max_f32_e32 v114, v119, v119
	v_max_f32_e32 v115, v115, v115
	v_max_f32_e32 v116, 0, v116
	v_mul_f32_e32 v112, v112, v112
	v_max_f32_e32 v113, 0, v113
	v_max_f32_e32 v114, 0, v114
	v_max_f32_e32 v115, 0, v115
	v_mul_f32_e32 v116, v116, v116
	v_mul_f32_e32 v113, v113, v113
	v_mul_f32_e32 v114, v114, v114
	v_mul_f32_e32 v115, v115, v115
	v_cvt_pk_bf16_f32 v112, v116, v112
	v_max_f32_e32 v104, v104, v104
	v_cvt_pk_bf16_f32 v113, v113, v114
	v_cvt_pk_bf16_f32 v114, v120, v117
	v_cvt_pk_bf16_f32 v115, v118, v115
	global_store_dwordx4 v[138:139], v[112:115], off offset:256 sc1
	v_max_f32_e32 v104, 0, v104
	v_max_f32_e32 v105, v105, v105
	v_or_b32_e32 v112, 16, v144
	v_max_f32_e32 v106, v106, v106
	v_ashrrev_i32_e32 v113, 31, v112
	v_mul_f32_e32 v114, v104, v104
	v_max_f32_e32 v104, v109, v109
	v_max_f32_e32 v105, 0, v105
	v_max_f32_e32 v106, 0, v106
	v_lshlrev_b64 v[112:113], 14, v[112:113]
	v_max_f32_e32 v108, v108, v108
	v_max_f32_e32 v104, 0, v104
	v_mul_f32_e32 v109, v105, v105
	v_max_f32_e32 v105, v110, v110
	v_mul_f32_e32 v110, v106, v106
	v_max_f32_e32 v106, v111, v111
	v_max_f32_e32 v107, v107, v107
	v_lshl_add_u64 v[112:113], s[2:3], 0, v[112:113]
	v_max_f32_e32 v108, 0, v108
	v_mul_f32_e32 v104, v104, v104
	v_max_f32_e32 v105, 0, v105
	v_max_f32_e32 v106, 0, v106
	v_max_f32_e32 v107, 0, v107
	v_max_f32_e32 v96, v96, v96
	v_lshl_add_u64 v[112:113], v[112:113], 0, v[148:149]
	v_mul_f32_e32 v108, v108, v108
	v_mul_f32_e32 v105, v105, v105
	v_mul_f32_e32 v106, v106, v106
	v_mul_f32_e32 v107, v107, v107
	v_cvt_pk_bf16_f32 v104, v108, v104
	v_max_f32_e32 v96, 0, v96
	v_max_f32_e32 v97, v97, v97
	v_max_f32_e32 v98, v98, v98
	v_cvt_pk_bf16_f32 v105, v105, v106
	v_cvt_pk_bf16_f32 v106, v114, v109
	v_cvt_pk_bf16_f32 v107, v110, v107
	global_store_dwordx4 v[112:113], v[104:107], off sc1
	v_max_f32_e32 v97, 0, v97
	v_max_f32_e32 v98, 0, v98
	v_mul_f32_e32 v104, v96, v96
	v_max_f32_e32 v96, v101, v101
	v_max_f32_e32 v100, v100, v100
	v_max_f32_e32 v96, 0, v96
	v_mul_f32_e32 v101, v97, v97
	v_max_f32_e32 v97, v102, v102
	v_mul_f32_e32 v102, v98, v98
	v_max_f32_e32 v98, v103, v103
	v_max_f32_e32 v99, v99, v99
	v_max_f32_e32 v100, 0, v100
	v_mul_f32_e32 v96, v96, v96
	v_max_f32_e32 v97, 0, v97
	v_max_f32_e32 v98, 0, v98
	v_max_f32_e32 v99, 0, v99
	v_mul_f32_e32 v100, v100, v100
	v_mul_f32_e32 v97, v97, v97
	v_mul_f32_e32 v98, v98, v98
	v_mul_f32_e32 v99, v99, v99
	v_cvt_pk_bf16_f32 v96, v100, v96
	v_max_f32_e32 v88, v88, v88
	v_cvt_pk_bf16_f32 v97, v97, v98
	v_cvt_pk_bf16_f32 v98, v104, v101
	v_cvt_pk_bf16_f32 v99, v102, v99
	global_store_dwordx4 v[112:113], v[96:99], off offset:256 sc1
	v_max_f32_e32 v88, 0, v88
	v_max_f32_e32 v89, v89, v89
	v_or_b32_e32 v96, 32, v144
	v_max_f32_e32 v90, v90, v90
	v_ashrrev_i32_e32 v97, 31, v96
	v_mul_f32_e32 v98, v88, v88
	v_max_f32_e32 v88, v93, v93
	v_max_f32_e32 v89, 0, v89
	v_max_f32_e32 v90, 0, v90
	v_lshlrev_b64 v[96:97], 14, v[96:97]
	v_max_f32_e32 v92, v92, v92
	v_max_f32_e32 v88, 0, v88
	v_mul_f32_e32 v93, v89, v89
	v_max_f32_e32 v89, v94, v94
	v_mul_f32_e32 v94, v90, v90
	v_max_f32_e32 v90, v95, v95
	v_max_f32_e32 v91, v91, v91
	v_lshl_add_u64 v[96:97], s[2:3], 0, v[96:97]
	v_max_f32_e32 v92, 0, v92
	v_mul_f32_e32 v88, v88, v88
	v_max_f32_e32 v89, 0, v89
	v_max_f32_e32 v90, 0, v90
	v_max_f32_e32 v91, 0, v91
	v_max_f32_e32 v80, v80, v80
	v_lshl_add_u64 v[96:97], v[96:97], 0, v[148:149]
	v_mul_f32_e32 v92, v92, v92
	v_mul_f32_e32 v89, v89, v89
	v_mul_f32_e32 v90, v90, v90
	v_mul_f32_e32 v91, v91, v91
	v_cvt_pk_bf16_f32 v88, v92, v88
	v_max_f32_e32 v80, 0, v80
	v_max_f32_e32 v81, v81, v81
	v_max_f32_e32 v82, v82, v82
	v_cvt_pk_bf16_f32 v89, v89, v90
	v_cvt_pk_bf16_f32 v90, v98, v93
	v_cvt_pk_bf16_f32 v91, v94, v91
	global_store_dwordx4 v[96:97], v[88:91], off sc1
	v_max_f32_e32 v81, 0, v81
	v_max_f32_e32 v82, 0, v82
	v_mul_f32_e32 v88, v80, v80
	v_max_f32_e32 v80, v85, v85
	v_max_f32_e32 v84, v84, v84
	v_max_f32_e32 v80, 0, v80
	v_mul_f32_e32 v85, v81, v81
	v_max_f32_e32 v81, v86, v86
	v_mul_f32_e32 v86, v82, v82
	v_max_f32_e32 v82, v87, v87
	v_max_f32_e32 v83, v83, v83
	v_max_f32_e32 v84, 0, v84
	v_mul_f32_e32 v80, v80, v80
	v_max_f32_e32 v81, 0, v81
	v_max_f32_e32 v82, 0, v82
	v_max_f32_e32 v83, 0, v83
	v_mul_f32_e32 v84, v84, v84
	v_mul_f32_e32 v81, v81, v81
	v_mul_f32_e32 v82, v82, v82
	v_mul_f32_e32 v83, v83, v83
	v_cvt_pk_bf16_f32 v80, v84, v80
	v_max_f32_e32 v72, v72, v72
	v_cvt_pk_bf16_f32 v81, v81, v82
	v_cvt_pk_bf16_f32 v82, v88, v85
	v_cvt_pk_bf16_f32 v83, v86, v83
	global_store_dwordx4 v[96:97], v[80:83], off offset:256 sc1
	v_max_f32_e32 v72, 0, v72
	v_max_f32_e32 v73, v73, v73
	v_or_b32_e32 v80, 48, v144
	v_max_f32_e32 v74, v74, v74
	v_ashrrev_i32_e32 v81, 31, v80
	v_mul_f32_e32 v82, v72, v72
	v_max_f32_e32 v72, v77, v77
	v_max_f32_e32 v73, 0, v73
	v_max_f32_e32 v74, 0, v74
	v_lshlrev_b64 v[80:81], 14, v[80:81]
	v_max_f32_e32 v76, v76, v76
	v_max_f32_e32 v72, 0, v72
	v_mul_f32_e32 v77, v73, v73
	v_max_f32_e32 v73, v78, v78
	v_mul_f32_e32 v78, v74, v74
	v_max_f32_e32 v74, v79, v79
	v_max_f32_e32 v75, v75, v75
	v_lshl_add_u64 v[80:81], s[2:3], 0, v[80:81]
	v_max_f32_e32 v76, 0, v76
	v_mul_f32_e32 v72, v72, v72
	v_max_f32_e32 v73, 0, v73
	v_max_f32_e32 v74, 0, v74
	v_max_f32_e32 v75, 0, v75
	v_max_f32_e32 v64, v64, v64
	v_max_f32_e32 v65, v65, v65
	v_max_f32_e32 v66, v66, v66
	v_lshl_add_u64 v[80:81], v[80:81], 0, v[148:149]
	v_mul_f32_e32 v76, v76, v76
	v_mul_f32_e32 v73, v73, v73
	v_mul_f32_e32 v74, v74, v74
	v_mul_f32_e32 v75, v75, v75
	v_cvt_pk_bf16_f32 v72, v76, v72
	v_max_f32_e32 v64, 0, v64
	v_max_f32_e32 v65, 0, v65
	v_max_f32_e32 v66, 0, v66
	v_cvt_pk_bf16_f32 v73, v73, v74
	v_cvt_pk_bf16_f32 v74, v82, v77
	v_cvt_pk_bf16_f32 v75, v78, v75
	global_store_dwordx4 v[80:81], v[72:75], off sc1
	v_max_f32_e32 v68, v68, v68
	v_max_f32_e32 v67, v67, v67
	v_mul_f32_e32 v72, v64, v64
	v_max_f32_e32 v64, v69, v69
	v_mul_f32_e32 v69, v65, v65
	v_max_f32_e32 v65, v70, v70
	v_mul_f32_e32 v70, v66, v66
	v_max_f32_e32 v66, v71, v71
	v_max_f32_e32 v64, 0, v64
	v_max_f32_e32 v65, 0, v65
	v_max_f32_e32 v66, 0, v66
	v_max_f32_e32 v68, 0, v68
	v_mul_f32_e32 v64, v64, v64
	v_mul_f32_e32 v65, v65, v65
	v_max_f32_e32 v67, 0, v67
	v_mul_f32_e32 v66, v66, v66
	v_max_f32_e32 v56, v56, v56
	v_mul_f32_e32 v68, v68, v68
	v_mul_f32_e32 v67, v67, v67
	v_cvt_pk_bf16_f32 v64, v68, v64
	v_cvt_pk_bf16_f32 v65, v65, v66
	v_cvt_pk_bf16_f32 v66, v72, v69
	v_max_f32_e32 v56, 0, v56
	v_max_f32_e32 v57, v57, v57
	v_max_f32_e32 v58, v58, v58
	v_cvt_pk_bf16_f32 v67, v70, v67
	global_store_dwordx4 v[80:81], v[64:67], off offset:256 sc1
	v_max_f32_e32 v60, v60, v60
	v_max_f32_e32 v57, 0, v57
	v_mul_f32_e32 v66, v56, v56
	v_max_f32_e32 v56, v61, v61
	v_max_f32_e32 v58, 0, v58
	s_mov_b64 s[2:3], 0x200000
	v_max_f32_e32 v60, 0, v60
	v_max_f32_e32 v56, 0, v56
	v_mul_f32_e32 v61, v57, v57
	v_max_f32_e32 v57, v62, v62
	v_mul_f32_e32 v62, v58, v58
	v_max_f32_e32 v58, v63, v63
	v_lshl_add_u64 v[64:65], v[138:139], 0, s[2:3]
	v_mul_f32_e32 v60, v60, v60
	v_mul_f32_e32 v56, v56, v56
	v_max_f32_e32 v57, 0, v57
	v_max_f32_e32 v58, 0, v58
	v_max_f32_e32 v59, v59, v59
	s_mov_b32 s2, 0x200000
	v_mul_f32_e32 v57, v57, v57
	v_max_f32_e32 v59, 0, v59
	v_mul_f32_e32 v58, v58, v58
	v_cvt_pk_bf16_f32 v56, v60, v56
	v_add_co_u32_e32 v60, vcc, s2, v138
	v_max_f32_e32 v48, v48, v48
	v_max_f32_e32 v49, v49, v49
	v_max_f32_e32 v50, v50, v50
	v_mul_f32_e32 v59, v59, v59
	v_cvt_pk_bf16_f32 v57, v57, v58
	v_cvt_pk_bf16_f32 v58, v66, v61
	v_addc_co_u32_e32 v61, vcc, 0, v139, vcc
	v_max_f32_e32 v48, 0, v48
	v_max_f32_e32 v49, 0, v49
	v_max_f32_e32 v50, 0, v50
	v_cvt_pk_bf16_f32 v59, v62, v59
	global_store_dwordx4 v[60:61], v[56:59], off sc1
	v_max_f32_e32 v52, v52, v52
	v_max_f32_e32 v51, v51, v51
	v_mul_f32_e32 v56, v48, v48
	v_max_f32_e32 v48, v53, v53
	v_mul_f32_e32 v53, v49, v49
	v_max_f32_e32 v49, v54, v54
	v_mul_f32_e32 v54, v50, v50
	v_max_f32_e32 v50, v55, v55
	v_max_f32_e32 v48, 0, v48
	v_max_f32_e32 v49, 0, v49
	v_max_f32_e32 v50, 0, v50
	v_max_f32_e32 v52, 0, v52
	v_mul_f32_e32 v48, v48, v48
	v_mul_f32_e32 v49, v49, v49
	v_max_f32_e32 v51, 0, v51
	v_mul_f32_e32 v50, v50, v50
	v_max_f32_e32 v40, v40, v40
	v_mul_f32_e32 v52, v52, v52
	v_mul_f32_e32 v51, v51, v51
	v_cvt_pk_bf16_f32 v48, v52, v48
	v_cvt_pk_bf16_f32 v49, v49, v50
	v_cvt_pk_bf16_f32 v50, v56, v53
	v_max_f32_e32 v40, 0, v40
	v_max_f32_e32 v41, v41, v41
	v_max_f32_e32 v42, v42, v42
	v_cvt_pk_bf16_f32 v51, v54, v51
	global_store_dwordx4 v[64:65], v[48:51], off offset:256 sc1
	v_max_f32_e32 v44, v44, v44
	v_max_f32_e32 v41, 0, v41
	v_mul_f32_e32 v50, v40, v40
	v_max_f32_e32 v40, v45, v45
	v_max_f32_e32 v42, 0, v42
	s_mov_b64 s[2:3], 0x240000
	v_max_f32_e32 v44, 0, v44
	v_max_f32_e32 v40, 0, v40
	v_mul_f32_e32 v45, v41, v41
	v_max_f32_e32 v41, v46, v46
	v_mul_f32_e32 v46, v42, v42
	v_max_f32_e32 v42, v47, v47
	v_lshl_add_u64 v[48:49], v[138:139], 0, s[2:3]
	v_mul_f32_e32 v44, v44, v44
	v_mul_f32_e32 v40, v40, v40
	v_max_f32_e32 v41, 0, v41
	v_max_f32_e32 v42, 0, v42
	v_max_f32_e32 v43, v43, v43
	s_mov_b32 s2, 0x240000
	v_mul_f32_e32 v41, v41, v41
	v_max_f32_e32 v43, 0, v43
	v_mul_f32_e32 v42, v42, v42
	v_cvt_pk_bf16_f32 v40, v44, v40
	v_add_co_u32_e32 v44, vcc, s2, v138
	v_max_f32_e32 v32, v32, v32
	v_max_f32_e32 v33, v33, v33
	v_max_f32_e32 v34, v34, v34
	v_mul_f32_e32 v43, v43, v43
	v_cvt_pk_bf16_f32 v41, v41, v42
	v_cvt_pk_bf16_f32 v42, v50, v45
	v_addc_co_u32_e32 v45, vcc, 0, v139, vcc
	v_max_f32_e32 v32, 0, v32
	v_max_f32_e32 v33, 0, v33
	v_max_f32_e32 v34, 0, v34
	v_cvt_pk_bf16_f32 v43, v46, v43
	global_store_dwordx4 v[44:45], v[40:43], off sc1
	v_max_f32_e32 v36, v36, v36
	v_max_f32_e32 v35, v35, v35
	v_mul_f32_e32 v40, v32, v32
	v_max_f32_e32 v32, v37, v37
	v_mul_f32_e32 v37, v33, v33
	v_max_f32_e32 v33, v38, v38
	v_mul_f32_e32 v38, v34, v34
	v_max_f32_e32 v34, v39, v39
	v_max_f32_e32 v32, 0, v32
	v_max_f32_e32 v33, 0, v33
	v_max_f32_e32 v34, 0, v34
	v_max_f32_e32 v36, 0, v36
	v_mul_f32_e32 v32, v32, v32
	v_mul_f32_e32 v33, v33, v33
	v_max_f32_e32 v35, 0, v35
	v_mul_f32_e32 v34, v34, v34
	v_max_f32_e32 v24, v24, v24
	v_mul_f32_e32 v36, v36, v36
	v_mul_f32_e32 v35, v35, v35
	v_cvt_pk_bf16_f32 v32, v36, v32
	v_cvt_pk_bf16_f32 v33, v33, v34
	v_cvt_pk_bf16_f32 v34, v40, v37
	v_max_f32_e32 v24, 0, v24
	v_max_f32_e32 v25, v25, v25
	v_max_f32_e32 v26, v26, v26
	v_cvt_pk_bf16_f32 v35, v38, v35
	global_store_dwordx4 v[48:49], v[32:35], off offset:256 sc1
	v_max_f32_e32 v28, v28, v28
	v_max_f32_e32 v25, 0, v25
	v_mul_f32_e32 v34, v24, v24
	v_max_f32_e32 v24, v29, v29
	v_max_f32_e32 v26, 0, v26
	s_mov_b64 s[2:3], 0x280000
	v_max_f32_e32 v28, 0, v28
	v_max_f32_e32 v24, 0, v24
	v_mul_f32_e32 v29, v25, v25
	v_max_f32_e32 v25, v30, v30
	v_mul_f32_e32 v30, v26, v26
	v_max_f32_e32 v26, v31, v31
	v_lshl_add_u64 v[32:33], v[138:139], 0, s[2:3]
	v_mul_f32_e32 v28, v28, v28
	v_mul_f32_e32 v24, v24, v24
	v_max_f32_e32 v25, 0, v25
	v_max_f32_e32 v26, 0, v26
	v_max_f32_e32 v27, v27, v27
	s_mov_b32 s2, 0x280000
	v_mul_f32_e32 v25, v25, v25
	v_max_f32_e32 v27, 0, v27
	v_mul_f32_e32 v26, v26, v26
	v_cvt_pk_bf16_f32 v24, v28, v24
	v_add_co_u32_e32 v28, vcc, s2, v138
	v_max_f32_e32 v16, v16, v16
	v_max_f32_e32 v17, v17, v17
	v_max_f32_e32 v18, v18, v18
	v_mul_f32_e32 v27, v27, v27
	v_cvt_pk_bf16_f32 v25, v25, v26
	v_cvt_pk_bf16_f32 v26, v34, v29
	v_addc_co_u32_e32 v29, vcc, 0, v139, vcc
	v_max_f32_e32 v16, 0, v16
	v_max_f32_e32 v17, 0, v17
	v_max_f32_e32 v18, 0, v18
	v_cvt_pk_bf16_f32 v27, v30, v27
	global_store_dwordx4 v[28:29], v[24:27], off sc1
	v_max_f32_e32 v20, v20, v20
	v_max_f32_e32 v19, v19, v19
	v_mul_f32_e32 v24, v16, v16
	v_max_f32_e32 v16, v21, v21
	v_mul_f32_e32 v21, v17, v17
	v_max_f32_e32 v17, v22, v22
	v_mul_f32_e32 v22, v18, v18
	v_max_f32_e32 v18, v23, v23
	v_max_f32_e32 v16, 0, v16
	v_max_f32_e32 v17, 0, v17
	v_max_f32_e32 v18, 0, v18
	v_max_f32_e32 v20, 0, v20
	v_mul_f32_e32 v16, v16, v16
	v_mul_f32_e32 v17, v17, v17
	v_max_f32_e32 v19, 0, v19
	v_mul_f32_e32 v18, v18, v18
	v_max_f32_e32 v8, v8, v8
	v_mul_f32_e32 v20, v20, v20
	v_mul_f32_e32 v19, v19, v19
	v_cvt_pk_bf16_f32 v16, v20, v16
	v_cvt_pk_bf16_f32 v17, v17, v18
	v_cvt_pk_bf16_f32 v18, v24, v21
	v_max_f32_e32 v8, 0, v8
	v_max_f32_e32 v9, v9, v9
	v_max_f32_e32 v10, v10, v10
	v_cvt_pk_bf16_f32 v19, v22, v19
	global_store_dwordx4 v[32:33], v[16:19], off offset:256 sc1
	v_max_f32_e32 v12, v12, v12
	v_max_f32_e32 v9, 0, v9
	v_mul_f32_e32 v18, v8, v8
	v_max_f32_e32 v8, v13, v13
	v_max_f32_e32 v10, 0, v10
	s_mov_b64 s[2:3], 0x2c0000
	v_max_f32_e32 v12, 0, v12
	v_max_f32_e32 v8, 0, v8
	v_mul_f32_e32 v13, v9, v9
	v_max_f32_e32 v9, v14, v14
	v_mul_f32_e32 v14, v10, v10
	v_max_f32_e32 v10, v15, v15
	v_lshl_add_u64 v[16:17], v[138:139], 0, s[2:3]
	v_mul_f32_e32 v12, v12, v12
	v_mul_f32_e32 v8, v8, v8
	v_max_f32_e32 v9, 0, v9
	v_max_f32_e32 v10, 0, v10
	v_max_f32_e32 v11, v11, v11
	s_mov_b32 s2, 0x2c0000
	v_mul_f32_e32 v9, v9, v9
	v_max_f32_e32 v11, 0, v11
	v_mul_f32_e32 v10, v10, v10
	v_cvt_pk_bf16_f32 v8, v12, v8
	v_add_co_u32_e32 v12, vcc, s2, v138
	v_max_f32_e32 v0, v0, v0
	v_max_f32_e32 v1, v1, v1
	v_max_f32_e32 v2, v2, v2
	v_mul_f32_e32 v11, v11, v11
	v_cvt_pk_bf16_f32 v9, v9, v10
	v_cvt_pk_bf16_f32 v10, v18, v13
	v_addc_co_u32_e32 v13, vcc, 0, v139, vcc
	v_max_f32_e32 v0, 0, v0
	v_max_f32_e32 v1, 0, v1
	v_max_f32_e32 v2, 0, v2
	v_cvt_pk_bf16_f32 v11, v14, v11
	global_store_dwordx4 v[12:13], v[8:11], off sc1
	v_max_f32_e32 v3, v3, v3
	v_max_f32_e32 v4, v4, v4
	v_mul_f32_e32 v8, v0, v0
	v_max_f32_e32 v0, v5, v5
	v_mul_f32_e32 v5, v1, v1
	v_max_f32_e32 v1, v6, v6
	v_mul_f32_e32 v6, v2, v2
	v_max_f32_e32 v2, v7, v7
	v_max_f32_e32 v0, 0, v0
	v_max_f32_e32 v1, 0, v1
	v_max_f32_e32 v2, 0, v2
	v_max_f32_e32 v3, 0, v3
	v_max_f32_e32 v4, 0, v4
	v_mul_f32_e32 v0, v0, v0
	v_mul_f32_e32 v1, v1, v1
	v_mul_f32_e32 v2, v2, v2
	v_mul_f32_e32 v3, v3, v3
	s_and_b64 vcc, exec, s[0:1]
	s_mov_b32 s67, s14
	s_mov_b32 s38, s28
	s_mov_b64 s[4:5], s[36:37]
	s_mov_b64 s[2:3], s[34:35]
	v_mul_f32_e32 v4, v4, v4
	v_cvt_pk_bf16_f32 v0, v4, v0
	v_cvt_pk_bf16_f32 v1, v1, v2
	v_cvt_pk_bf16_f32 v2, v8, v5
	v_cvt_pk_bf16_f32 v3, v6, v3
	global_store_dwordx4 v[16:17], v[0:3], off offset:256 sc1
	s_cbranch_vccz .LBB0_253
	s_waitcnt vmcnt(0)
	v_readlane_b32 s62, v254, 59
	s_cmpk_gt_u32 s41, 0xff
	v_readlane_b32 s55, v254, 57
	v_readlane_b32 s58, v254, 58
	v_readlane_b32 s63, v254, 60
	v_readlane_b32 s59, v255, 1
	s_movk_i32 s66, 0x3000
	v_readlane_b32 s49, v255, 18
	s_cbranch_scc1 .LBB0_260
	s_barrier
